# v31 + MLA start without the z tiles (z polled at the epilogue) + MLA silu(z) loads in front of the epilogue barrier
# speedup vs baseline: 1.0017x; 1.0017x over previous
.Lmz_done:
	s_ashr_i32 s0, s5, 8
	s_add_i32 s0, s0, s79
	s_lshl_b32 s28, s0, 2
	s_ashr_i32 s29, s28, 31
	s_lshl_b64 s[28:29], s[28:29], 2
	s_add_u32 s64, s39, s28
	s_addc_u32 s65, s8, s29
	s_lshl_b32 s0, s2, 6
	s_add_i32 s60, s0, 0x280
	v_ashrrev_i32_e32 v56, 3, v80
	s_add_i32 s5, s5, s51
	s_lshl_b64 s[28:29], s[60:61], 1
	v_lshlrev_b32_e32 v17, 3, v80
	s_waitcnt lgkmcnt(0)
	v_add_u32_e32 v16, s5, v56
	s_add_u32 s2, s18, s28
	v_and_b32_e32 v57, 56, v17
	s_addc_u32 s3, s19, s29
	v_lshlrev_b32_e32 v80, 1, v57
	v_ashrrev_i32_e32 v17, 31, v16
	v_lshl_add_u64 v[18:19], s[2:3], 0, v[80:81]
	v_lshlrev_b64 v[54:55], 11, v[16:17]
	v_lshl_add_u64 v[20:21], v[18:19], 0, v[54:55]
	global_load_dwordx4 v[28:31], v[20:21], off
	v_add_u32_e32 v20, 8, v16
	v_ashrrev_i32_e32 v21, 31, v20
	v_lshlrev_b64 v[52:53], 11, v[20:21]
	v_lshl_add_u64 v[20:21], v[18:19], 0, v[52:53]
	global_load_dwordx4 v[24:27], v[20:21], off
	v_add_u32_e32 v20, 16, v16
	v_ashrrev_i32_e32 v21, 31, v20
	v_lshlrev_b64 v[50:51], 11, v[20:21]
	v_lshl_add_u64 v[20:21], v[18:19], 0, v[50:51]
	global_load_dwordx4 v[20:23], v[20:21], off
	v_add_u32_e32 v16, 24, v16
	v_ashrrev_i32_e32 v17, 31, v16
	v_lshlrev_b64 v[48:49], 11, v[16:17]
	v_lshl_add_u64 v[16:17], v[18:19], 0, v[48:49]
	global_load_dwordx4 v[16:19], v[16:17], off
	s_barrier
	s_movk_i32 s0, 0x440
	v_lshlrev_b32_e32 v58, 2, v131
	v_mul_lo_u32 v59, v130, s0
	v_add3_u32 v58, s9, v58, v59
	ds_write2_b32 v58, v0, v32 offset1:32
	ds_write2_b32 v58, v1, v33 offset0:68 offset1:100
	ds_write2_b32 v58, v2, v34 offset0:136 offset1:168
	ds_write2_b32 v58, v3, v35 offset0:204 offset1:236
	v_add_u32_e32 v0, 0x800, v58
	ds_write2_b32 v0, v4, v36 offset0:32 offset1:64
	ds_write2_b32 v0, v5, v37 offset0:100 offset1:132
	ds_write2_b32 v0, v6, v38 offset0:168 offset1:200
	v_add_u32_e32 v0, 0xa00, v58
	ds_write2_b32 v0, v7, v39 offset0:108 offset1:140
	v_add_u32_e32 v0, 0x1000, v58
	ds_write2_b32 v0, v8, v40 offset0:64 offset1:96
	ds_write2_b32 v0, v9, v41 offset0:132 offset1:164
	ds_write2_b32 v0, v10, v42 offset0:200 offset1:232
	v_add_u32_e32 v0, 0x1400, v58
	ds_write2_b32 v0, v11, v43 offset0:12 offset1:44
	v_add_u32_e32 v0, 0x1800, v58
	ds_write2_b32 v0, v12, v44 offset0:96 offset1:128
	ds_write2_b32 v0, v13, v45 offset0:164 offset1:196
	v_add_u32_e32 v0, 0x1a00, v58
	ds_write2_b32 v0, v14, v46 offset0:104 offset1:136
	v_add_u32_e32 v0, 0x1c00, v58
	ds_write2_b32 v0, v15, v47 offset0:44 offset1:76
	v_lshlrev_b32_e32 v0, 2, v57
	v_mul_lo_u32 v1, v56, s77
	v_add3_u32 v9, s9, v0, v1
	v_lshl_add_u32 v12, v56, 2, s6
	s_waitcnt lgkmcnt(0)
	ds_read_b128 v[0:3], v9
	ds_read_b128 v[4:7], v9 offset:16
	ds_read_b32 v8, v12
	s_mov_b64 s[40:41], s[42:43]
	s_waitcnt lgkmcnt(0)
	v_pk_mul_f32 v[0:1], v[0:1], v[8:9] op_sel_hi:[1,0]
	v_pk_mul_f32 v[2:3], v[2:3], v[8:9] op_sel_hi:[1,0]
	s_waitcnt vmcnt(0)
	v_lshlrev_b32_e32 v10, 16, v28
	v_and_b32_e32 v11, 0xffff0000, v28
	v_pk_mul_f32 v[0:1], v[0:1], v[10:11]
	v_lshlrev_b32_e32 v10, 16, v29
	v_and_b32_e32 v11, 0xffff0000, v29
	v_pk_mul_f32 v[2:3], v[2:3], v[10:11]
	v_cvt_pk_bf16_f32 v0, v0, v1
	v_cvt_pk_bf16_f32 v1, v2, v3
	v_pk_mul_f32 v[2:3], v[4:5], v[8:9] op_sel_hi:[1,0]
	v_lshlrev_b32_e32 v4, 16, v30
	v_and_b32_e32 v5, 0xffff0000, v30
	v_pk_mul_f32 v[2:3], v[2:3], v[4:5]
	v_pk_mul_f32 v[4:5], v[6:7], v[8:9] op_sel_hi:[1,0]
	v_lshlrev_b32_e32 v6, 16, v31
	v_and_b32_e32 v7, 0xffff0000, v31
	v_pk_mul_f32 v[4:5], v[4:5], v[6:7]
	v_cvt_pk_bf16_f32 v2, v2, v3
	v_cvt_pk_bf16_f32 v3, v4, v5
	v_lshl_add_u64 v[4:5], s[26:27], 0, v[54:55]
	v_lshl_add_u64 v[4:5], v[4:5], 0, s[28:29]
	v_lshl_add_u64 v[4:5], v[4:5], 0, v[80:81]
	global_store_dwordx4 v[4:5], v[0:3], off sc1
	s_nop 1
	ds_read_b128 v[0:3], v9 offset:2176
	ds_read_b128 v[4:7], v9 offset:2192
	ds_read_b32 v8, v12 offset:32
	v_lshlrev_b32_e32 v10, 16, v24
	v_and_b32_e32 v11, 0xffff0000, v24
	s_waitcnt lgkmcnt(0)
	v_pk_mul_f32 v[0:1], v[0:1], v[8:9] op_sel_hi:[1,0]
	s_nop 0
	v_pk_mul_f32 v[0:1], v[0:1], v[10:11]
	v_pk_mul_f32 v[2:3], v[2:3], v[8:9] op_sel_hi:[1,0]
	v_lshlrev_b32_e32 v10, 16, v25
	v_and_b32_e32 v11, 0xffff0000, v25
	v_pk_mul_f32 v[2:3], v[2:3], v[10:11]
	v_cvt_pk_bf16_f32 v0, v0, v1
	v_cvt_pk_bf16_f32 v1, v2, v3
	v_pk_mul_f32 v[2:3], v[4:5], v[8:9] op_sel_hi:[1,0]
	v_lshlrev_b32_e32 v4, 16, v26
	v_and_b32_e32 v5, 0xffff0000, v26
	v_pk_mul_f32 v[2:3], v[2:3], v[4:5]
	v_pk_mul_f32 v[4:5], v[6:7], v[8:9] op_sel_hi:[1,0]
	v_lshlrev_b32_e32 v6, 16, v27
	v_and_b32_e32 v7, 0xffff0000, v27
	v_pk_mul_f32 v[4:5], v[4:5], v[6:7]
	v_cvt_pk_bf16_f32 v2, v2, v3
	v_cvt_pk_bf16_f32 v3, v4, v5
	v_lshl_add_u64 v[4:5], s[26:27], 0, v[52:53]
	v_lshl_add_u64 v[4:5], v[4:5], 0, s[28:29]
	v_lshl_add_u64 v[4:5], v[4:5], 0, v[80:81]
	global_store_dwordx4 v[4:5], v[0:3], off sc1
	s_nop 1
	ds_read_b128 v[0:3], v9 offset:4352
	ds_read_b128 v[4:7], v9 offset:4368
	ds_read_b32 v8, v12 offset:64
	v_lshlrev_b32_e32 v10, 16, v20
	v_and_b32_e32 v11, 0xffff0000, v20
	s_waitcnt lgkmcnt(0)
	v_pk_mul_f32 v[0:1], v[0:1], v[8:9] op_sel_hi:[1,0]
	s_nop 0
	v_pk_mul_f32 v[0:1], v[0:1], v[10:11]
	v_pk_mul_f32 v[2:3], v[2:3], v[8:9] op_sel_hi:[1,0]
	v_lshlrev_b32_e32 v10, 16, v21
	v_and_b32_e32 v11, 0xffff0000, v21
	v_pk_mul_f32 v[2:3], v[2:3], v[10:11]
	v_cvt_pk_bf16_f32 v0, v0, v1
	v_cvt_pk_bf16_f32 v1, v2, v3
	v_pk_mul_f32 v[2:3], v[4:5], v[8:9] op_sel_hi:[1,0]
	v_lshlrev_b32_e32 v4, 16, v22
	v_and_b32_e32 v5, 0xffff0000, v22
	v_pk_mul_f32 v[2:3], v[2:3], v[4:5]
	v_pk_mul_f32 v[4:5], v[6:7], v[8:9] op_sel_hi:[1,0]
	v_lshlrev_b32_e32 v6, 16, v23
	v_and_b32_e32 v7, 0xffff0000, v23
	v_pk_mul_f32 v[4:5], v[4:5], v[6:7]
	v_cvt_pk_bf16_f32 v2, v2, v3
	v_cvt_pk_bf16_f32 v3, v4, v5
	v_lshl_add_u64 v[4:5], s[26:27], 0, v[50:51]
	v_lshl_add_u64 v[4:5], v[4:5], 0, s[28:29]
	v_lshl_add_u64 v[4:5], v[4:5], 0, v[80:81]
	global_store_dwordx4 v[4:5], v[0:3], off sc1
	s_nop 1
	ds_read_b128 v[0:3], v9 offset:6528
	ds_read_b128 v[4:7], v9 offset:6544
	ds_read_b32 v8, v12 offset:96
	v_lshlrev_b32_e32 v10, 16, v16
	v_and_b32_e32 v11, 0xffff0000, v16
	s_waitcnt lgkmcnt(0)
	v_pk_mul_f32 v[0:1], v[0:1], v[8:9] op_sel_hi:[1,0]
	s_nop 0
	v_pk_mul_f32 v[0:1], v[0:1], v[10:11]
	v_pk_mul_f32 v[2:3], v[2:3], v[8:9] op_sel_hi:[1,0]
	v_lshlrev_b32_e32 v10, 16, v17
	v_and_b32_e32 v11, 0xffff0000, v17
	v_pk_mul_f32 v[2:3], v[2:3], v[10:11]
	v_cvt_pk_bf16_f32 v0, v0, v1
	v_cvt_pk_bf16_f32 v1, v2, v3
	v_pk_mul_f32 v[2:3], v[4:5], v[8:9] op_sel_hi:[1,0]
	v_lshlrev_b32_e32 v4, 16, v18
	v_and_b32_e32 v5, 0xffff0000, v18
	v_pk_mul_f32 v[2:3], v[2:3], v[4:5]
	v_pk_mul_f32 v[4:5], v[6:7], v[8:9] op_sel_hi:[1,0]
	v_lshlrev_b32_e32 v6, 16, v19
	v_and_b32_e32 v7, 0xffff0000, v19
	v_pk_mul_f32 v[4:5], v[4:5], v[6:7]
	v_cvt_pk_bf16_f32 v2, v2, v3
	v_cvt_pk_bf16_f32 v3, v4, v5
	v_lshl_add_u64 v[4:5], s[26:27], 0, v[48:49]
	v_lshl_add_u64 v[4:5], v[4:5], 0, s[28:29]
	v_lshl_add_u64 v[4:5], v[4:5], 0, v[80:81]
	global_store_dwordx4 v[4:5], v[0:3], off sc1
	s_nop 1
	s_waitcnt vmcnt(0)
	s_barrier
